# sa2 + DMA scalar base maintained incrementally (two scalar adds per piece instead of four)
# speedup vs baseline: 1.0048x; 1.0048x over previous
; #define TWAIT_BAR(N) asm volatile("s_waitcnt vmcnt(" #N ") lgkmcnt(0)\n\ts_barrier" ::: "memory")
; #define TMX3(a, b, c) __builtin_fmaxf(__builtin_fmaxf((a), (b)), (c))
; #define TEX(v) __builtin_amdgcn_exp2f(v)
; #define DMA_K(t, slot) glds16(ksrc + (size_t)(t) * 64 * 512, (unsigned)__builtin_amdgcn_readfirstlane(kdst + (slot)))
; #define DMA_V(t, slot) glds16(vsrc + (size_t)(t) * 64 * 512, (unsigned)__builtin_amdgcn_readfirstlane(vdst + (slot)))
; #define ROT() do { sl_prev = sl_cur; sl_cur = sl_next; sl_next = (sl_next == 2 * SLOTB) ? 0 : sl_next + SLOTB; } while (0)
; #define DMA_K(t, slot) glds16(ksrc + (size_t)(t) * 64 * 512, (unsigned)__builtin_amdgcn_readfirstlane(kdst + (slot)))
; #define DMA_V(t, slot) do { glds16(vsrc + (size_t)(t) * 64 * 512, (unsigned)__builtin_amdgcn_readfirstlane(vdst + (slot))); glds16(vsrc + (size_t)(t) * 64 * 512 + 64, (unsigned)__builtin_amdgcn_readfirstlane(vdst + (slot) + 8192)); } while (0)
; #define ROT() do { sl_prev = sl_cur; sl_cur = sl_next; sl_next = (sl_next == 2) ? 0 : sl_next + 1; } while (0)
; template <bool NOMAX>
; __device__ __forceinline__ void diff_unit(const AttnCtx& C, int u, LAS unsigned char* lds) {
;     ...
;         if constexpr (NOMAX) {
; #pragma unroll
;             for (int r = 0; r < 16; ++r) { pA0[r] = TEX(pA0[r]); pA1[r] = TEX(pA1[r]); }
;         } else {
;         float rm = TMX3(pA0[0], pA0[1], pA1[0]);
; #pragma unroll
;         for (int r = 1; r < 16; ++r) rm = TMX3(rm, pA0[r], pA1[r]);
;         { auto rr = __builtin_amdgcn_permlane32_swap(__float_as_uint(rm), __float_as_uint(rm), false, false); rm = __builtin_fmaxf(__uint_as_float(rr[0]), __uint_as_float(rr[1])); }
;         nm -= rm;
; #pragma unroll
;         for (int r = 0; r < 16; ++r) { pA0[r] = TEX(pA0[r] - rm); pA1[r] = TEX(pA1[r] - rm); }
;         }
;     }
;     TWAIT_BAR(0);
;     DMA_K(3, 0); DMA_V(1, VSLOT);
;     ROT();
;     kload8(kf, kp0 + sl_cur * SLOTB);
;     TWAIT_BAR(3);
;     s16x4 vl0, vh0, vl1, vh1, vl2, vh2, vl3, vh3; v4u pw0, pw1, pw2, pw3;
;     bf16x8 qa = QRD(0), qb_;
.LBB0_461:
	v_lshlrev_b32_e32 v2, 1, v6
	v_and_b32_e32 v2, 32, v2
	v_lshlrev_b32_e32 v8, 4, v6
	v_add3_u32 v2, 0, v2, v7
	v_lshlrev_b32_e32 v7, 8, v211
	v_and_b32_e32 v8, 0xc0, v8
	s_waitcnt vmcnt(0) lgkmcnt(0)
	s_barrier
	v_add3_u32 v214, v2, v7, v8
	v_lshl_add_u64 v[8:9], v[204:205], 0, s[24:25]
	s_mov_b32 s6, m0
	s_mov_b32 m0, s49
	s_nop 0
	global_load_lds_dwordx4 v[8:9], off
	s_mov_b32 m0, s6
	v_lshl_add_u64 v[8:9], v[4:5], 0, s[20:21]
	s_add_i32 s6, s49, 0xa000
	s_mov_b32 s7, m0
	s_mov_b32 m0, s6
	s_nop 0
	global_load_lds_dwordx4 v[8:9], off
	s_mov_b32 m0, s7
	v_lshl_add_u64 v[4:5], v[4:5], 0, s[26:27]
	s_add_i32 s6, s49, 0xc000
	s_mov_b32 s7, m0
	s_mov_b32 m0, s6
	s_nop 0
	global_load_lds_dwordx4 v[4:5], off
	s_mov_b32 m0, s7
	ds_read_b128 v[192:195], v222 offset:8192
	ds_read_b128 v[184:187], v222 offset:8704
	ds_read_b128 v[188:191], v222 offset:10240
	ds_read_b128 v[180:183], v222 offset:10752
	ds_read_b128 v[176:179], v222 offset:12288
	ds_read_b128 v[172:175], v222 offset:12800
	ds_read_b128 v[168:171], v222 offset:14336
	ds_read_b128 v[164:167], v222 offset:14848
	s_waitcnt vmcnt(3) lgkmcnt(0)
	s_barrier
	ds_read_b128 v[116:119], v219
	v_exp_f32_e32 v100, v36
	v_exp_f32_e32 v84, v20
	v_exp_f32_e32 v101, v37
	v_exp_f32_e32 v85, v21
	v_exp_f32_e32 v102, v38
	v_exp_f32_e32 v86, v22
	v_exp_f32_e32 v103, v39
	v_exp_f32_e32 v87, v23
	v_exp_f32_e32 v104, v40
	v_exp_f32_e32 v88, v24
	v_exp_f32_e32 v105, v41
	v_exp_f32_e32 v89, v25
	v_exp_f32_e32 v106, v42
	v_exp_f32_e32 v90, v26
	v_exp_f32_e32 v107, v43
	v_exp_f32_e32 v91, v27
	v_exp_f32_e32 v108, v44
	v_exp_f32_e32 v92, v28
	v_exp_f32_e32 v109, v45
	v_exp_f32_e32 v93, v29
	v_exp_f32_e32 v110, v46
	v_exp_f32_e32 v94, v30
	v_exp_f32_e32 v111, v47
	v_exp_f32_e32 v95, v31
	v_exp_f32_e32 v112, v48
	v_exp_f32_e32 v96, v32
	v_exp_f32_e32 v113, v49
	v_exp_f32_e32 v97, v33
	v_exp_f32_e32 v114, v50
	v_exp_f32_e32 v98, v34
	v_exp_f32_e32 v115, v51
	v_exp_f32_e32 v99, v35
	v_cmp_gt_u32_e32 vcc, 2, v224
	v_and_b32_e32 v2, 3, v6
	s_mov_b32 s59, 1
	v_add_u32_e32 v226, 4, v234
	s_mov_b32 s60, 2
	v_lshlrev_b32_e32 v206, 4, v2
	s_cbranch_vccnz .LBB0_466
	v_mov_b32_e32 v221, v3
	s_lshl_b64 s[6:7], s[4:5], 1
	v_lshl_add_u64 v[4:5], s[6:7], 0, v[220:221]
	s_lshl_b32 s6, s1, 8
	v_mov_b32_e32 v207, v3
	s_and_b32 s6, s6, 0xc000
	v_lshl_add_u64 v[4:5], v[4:5], 0, v[206:207]
	v_lshl_or_b32 v2, v208, 10, s6
	v_lshl_add_u64 v[4:5], v[4:5], 0, v[2:3]
	v_mov_b32_e32 v225, 0
	s_mov_b32 s16, 8
	v_lshl_add_u64 v[8:9], s[94:95], 0, v[4:5]
	s_mov_b32 s11, 0
	s_mov_b64 s[6:7], 0
	v_mov_b32_e32 v68, 0
	v_mov_b32_e32 v69, v225
	v_mov_b32_e32 v70, v225
	v_mov_b32_e32 v71, v225
	v_mov_b32_e32 v72, v225
	v_mov_b32_e32 v73, v225
	v_mov_b32_e32 v74, v225
	v_mov_b32_e32 v75, v225
	v_mov_b32_e32 v76, v225
	v_mov_b32_e32 v77, v225
	v_mov_b32_e32 v78, v225
	v_mov_b32_e32 v79, v225
	v_mov_b32_e32 v80, v225
	v_mov_b32_e32 v81, v225
	v_mov_b32_e32 v82, v225
	v_mov_b32_e32 v83, v225
	v_mov_b32_e32 v52, 0
	v_mov_b32_e32 v53, v225
	v_mov_b32_e32 v54, v225
	v_mov_b32_e32 v55, v225
	v_mov_b32_e32 v56, v225
	v_mov_b32_e32 v57, v225
	v_mov_b32_e32 v58, v225
	v_mov_b32_e32 v59, v225
	v_mov_b32_e32 v60, v225
	v_mov_b32_e32 v61, v225
	v_mov_b32_e32 v62, v225
	v_mov_b32_e32 v63, v225
	v_mov_b32_e32 v64, v225
	v_mov_b32_e32 v65, v225
	v_mov_b32_e32 v66, v225
	v_mov_b32_e32 v67, v225
	v_mov_b32_e32 v36, 0
	v_mov_b32_e32 v37, v225
	v_mov_b32_e32 v38, v225
	v_mov_b32_e32 v39, v225
	v_mov_b32_e32 v40, v225
	v_mov_b32_e32 v41, v225
	v_mov_b32_e32 v42, v225
	v_mov_b32_e32 v43, v225
	v_mov_b32_e32 v44, v225
	v_mov_b32_e32 v45, v225
	v_mov_b32_e32 v46, v225
	v_mov_b32_e32 v47, v225
	v_mov_b32_e32 v48, v225
	v_mov_b32_e32 v49, v225
	v_mov_b32_e32 v50, v225
	v_mov_b32_e32 v51, v225
	v_mov_b32_e32 v20, 0
	v_mov_b32_e32 v21, v225
	v_mov_b32_e32 v22, v225
	v_mov_b32_e32 v23, v225
	v_mov_b32_e32 v24, v225
	v_mov_b32_e32 v25, v225
	v_mov_b32_e32 v26, v225
	v_mov_b32_e32 v27, v225
	v_mov_b32_e32 v28, v225
	v_mov_b32_e32 v29, v225
	v_mov_b32_e32 v30, v225
	v_mov_b32_e32 v31, v225
	v_mov_b32_e32 v32, v225
	v_mov_b32_e32 v33, v225
	v_mov_b32_e32 v34, v225
	v_mov_b32_e32 v35, v225
	v_readfirstlane_b32 s100, v8
	v_readfirstlane_b32 s101, v9
	s_nop 1
	v_subrev_u32_e32 v255, s100, v8
	v_subrev_u32_e32 v254, s100, v204
	s_add_u32 s100, s100, s6
	s_addc_u32 s101, s101, s7
.LBB0_463:
	s_mov_b32 s8, s60
	s_mov_b32 s9, s16
	s_mov_b32 s10, s59
	ds_read_b128 v[4:7], v219 offset:1024
	v_lshl_add_u32 v207, s11, 14, v214
	v_add_f32_e32 v2, v100, v101
	v_add_f32_e32 v2, v102, v2
	v_add_f32_e32 v2, v103, v2
	v_add_f32_e32 v2, v104, v2
	v_add_f32_e32 v2, v105, v2
	v_cvt_pk_bf16_f32 v160, v100, v101
	v_cvt_pk_bf16_f32 v161, v102, v103
	s_waitcnt lgkmcnt(1)
	v_mfma_f32_32x32x16_bf16 v[132:147], v[192:195], v[116:119], 0
	v_mfma_f32_32x32x16_bf16 v[116:131], v[184:187], v[116:119], 0
	v_add_f32_e32 v2, v106, v2
	v_add_f32_e32 v2, v107, v2
	v_add_f32_e32 v2, v108, v2
	v_add_f32_e32 v2, v109, v2
	v_cvt_pk_bf16_f32 v162, v104, v105
	v_cvt_pk_bf16_f32 v163, v106, v107
	ds_read_b128 v[10:13], v219 offset:2048
	ds_read_b64_tr_b16 v[14:15], v207 offset:24576
	ds_read_b64_tr_b16 v[16:17], v207 offset:25088
	v_add_f32_e32 v2, v110, v2
	v_add_f32_e32 v2, v111, v2
	v_add_f32_e32 v2, v112, v2
	v_add_f32_e32 v2, v113, v2
	v_cvt_pk_bf16_f32 v156, v108, v109
	v_cvt_pk_bf16_f32 v157, v110, v111
	s_waitcnt lgkmcnt(3)
	v_mfma_f32_32x32x16_bf16 v[132:147], v[188:191], v[4:7], v[132:147]
	v_mfma_f32_32x32x16_bf16 v[116:131], v[180:183], v[4:7], v[116:131]
	v_add_f32_e32 v2, v114, v2
	v_add_f32_e32 v2, v115, v2
	v_add_f32_e32 v2, v84, v2
	v_add_f32_e32 v2, v85, v2
	v_cvt_pk_bf16_f32 v158, v112, v113
	v_cvt_pk_bf16_f32 v159, v114, v115
	ds_read_b128 v[4:7], v219 offset:3072
	ds_read_b64_tr_b16 v[100:101], v207 offset:28672
	ds_read_b64_tr_b16 v[102:103], v207 offset:29184
	v_add_f32_e32 v2, v86, v2
	v_add_f32_e32 v2, v87, v2
	v_add_f32_e32 v2, v88, v2
	v_add_f32_e32 v2, v89, v2
	v_cvt_pk_bf16_f32 v152, v84, v85
	v_cvt_pk_bf16_f32 v153, v86, v87
	s_waitcnt lgkmcnt(5)
	v_mfma_f32_32x32x16_bf16 v[132:147], v[176:179], v[10:13], v[132:147]
	v_mfma_f32_32x32x16_bf16 v[116:131], v[172:175], v[10:13], v[116:131]
	v_add_f32_e32 v2, v90, v2
	v_add_f32_e32 v2, v91, v2
	v_add_f32_e32 v2, v92, v2
	v_add_f32_e32 v2, v93, v2
	v_cvt_pk_bf16_f32 v154, v88, v89
	v_cvt_pk_bf16_f32 v155, v90, v91
	ds_read_b64_tr_b16 v[84:85], v207 offset:25600
	ds_read_b64_tr_b16 v[86:87], v207 offset:26112
	v_add_f32_e32 v2, v94, v2
	v_add_f32_e32 v2, v95, v2
	v_add_f32_e32 v2, v96, v2
	v_add_f32_e32 v2, v97, v2
	v_cvt_pk_bf16_f32 v148, v92, v93
	v_cvt_pk_bf16_f32 v149, v94, v95
	s_waitcnt lgkmcnt(4)
	v_mfma_f32_32x32x16_bf16 v[132:147], v[168:171], v[4:7], v[132:147]
	v_mfma_f32_32x32x16_bf16 v[116:131], v[164:167], v[4:7], v[116:131]
	v_add_f32_e32 v2, v98, v2
	v_add_f32_e32 v2, v99, v2
	v_cvt_pk_bf16_f32 v150, v96, v97
	v_cvt_pk_bf16_f32 v151, v98, v99
	v_add_f32_e32 v2, v225, v2
	ds_read_b64_tr_b16 v[4:5], v207 offset:29696
	ds_read_b64_tr_b16 v[6:7], v207 offset:30208
	v_mfma_f32_32x32x16_bf16 v[68:83], v[160:163], v[14:17], v[68:83]
	v_exp_f32_e32 v132, v132
	v_exp_f32_e32 v133, v133
	ds_read_b64_tr_b16 v[14:15], v207 offset:26624
	ds_read_b64_tr_b16 v[16:17], v207 offset:27136
	s_waitcnt lgkmcnt(6)
	v_mfma_f32_32x32x16_bf16 v[52:67], v[160:163], v[100:103], v[52:67]
	v_exp_f32_e32 v134, v134
	v_exp_f32_e32 v135, v135
	s_add_u32 s98, s100, s28
	s_addc_u32 s99, s101, s29
	s_lshl_b32 m0, s59, 13
	s_add_i32 m0, m0, s49
	s_nop 0
	global_load_lds_dwordx4 v254, s[98:99]
	ds_read_b64_tr_b16 v[88:89], v207 offset:30720
	ds_read_b64_tr_b16 v[90:91], v207 offset:31232
	s_waitcnt lgkmcnt(6)
	v_mfma_f32_32x32x16_bf16 v[68:83], v[156:159], v[84:87], v[68:83]
	v_exp_f32_e32 v136, v136
	v_exp_f32_e32 v137, v137
	ds_read_b64_tr_b16 v[84:85], v207 offset:27648
	ds_read_b64_tr_b16 v[86:87], v207 offset:28160
	s_waitcnt lgkmcnt(6)
	v_mfma_f32_32x32x16_bf16 v[52:67], v[156:159], v[4:7], v[52:67]
	v_exp_f32_e32 v138, v138
	v_exp_f32_e32 v139, v139
	ds_read_b64_tr_b16 v[4:5], v207 offset:31744
	ds_read_b64_tr_b16 v[6:7], v207 offset:32256
	s_waitcnt lgkmcnt(6)
	v_mfma_f32_32x32x16_bf16 v[68:83], v[152:155], v[14:17], v[68:83]
	v_exp_f32_e32 v140, v140
	v_exp_f32_e32 v141, v141
	s_add_u32 s98, s100, s30
	s_addc_u32 s99, s101, s31
	s_lshl_b32 m0, s60, 14
	s_add_i32 m0, m0, s58
	s_nop 0
	global_load_lds_dwordx4 v255, s[98:99]
	ds_read_b64_tr_b16 v[14:15], v207 offset:32768
	ds_read_b64_tr_b16 v[16:17], v207 offset:33280
	s_waitcnt lgkmcnt(6)
	v_mfma_f32_32x32x16_bf16 v[52:67], v[152:155], v[88:91], v[52:67]
	v_exp_f32_e32 v142, v142
	v_exp_f32_e32 v143, v143
	ds_read_b64_tr_b16 v[88:89], v207 offset:36864
	ds_read_b64_tr_b16 v[90:91], v207 offset:37376
	s_waitcnt lgkmcnt(6)
	v_mfma_f32_32x32x16_bf16 v[68:83], v[148:151], v[84:87], v[68:83]
	v_exp_f32_e32 v144, v144
	v_exp_f32_e32 v145, v145
	ds_read_b64_tr_b16 v[84:85], v207 offset:33792
	ds_read_b64_tr_b16 v[86:87], v207 offset:34304
	s_waitcnt lgkmcnt(6)
	v_mfma_f32_32x32x16_bf16 v[52:67], v[148:151], v[4:7], v[52:67]
	v_exp_f32_e32 v146, v146
	v_exp_f32_e32 v147, v147
	ds_read_b64_tr_b16 v[92:93], v207 offset:37888
	ds_read_b64_tr_b16 v[94:95], v207 offset:38400
	s_lshl_b32 s11, s60, 13
	v_add_u32_e32 v4, s11, v222
	ds_read_b128 v[96:99], v4
	ds_read_b128 v[164:167], v4 offset:512
	s_waitcnt lgkmcnt(8)
	v_mfma_f32_32x32x16_bf16 v[36:51], v[160:163], v[14:17], v[36:51]
	v_exp_f32_e32 v116, v116
	v_exp_f32_e32 v117, v117
	ds_read_b64_tr_b16 v[14:15], v207 offset:34816
	ds_read_b64_tr_b16 v[16:17], v207 offset:35328
	ds_read_b128 v[168:171], v4 offset:2048
	ds_read_b128 v[172:175], v4 offset:2560
	s_waitcnt lgkmcnt(10)
	v_mfma_f32_32x32x16_bf16 v[20:35], v[160:163], v[88:91], v[20:35]
	v_exp_f32_e32 v118, v118
	v_exp_f32_e32 v119, v119
	ds_read_b64_tr_b16 v[88:89], v207 offset:38912
	ds_read_b64_tr_b16 v[90:91], v207 offset:39424
	ds_read_b128 v[176:179], v4 offset:4096
	ds_read_b128 v[180:183], v4 offset:4608
	s_waitcnt lgkmcnt(12)
	v_mfma_f32_32x32x16_bf16 v[36:51], v[156:159], v[84:87], v[36:51]
	v_exp_f32_e32 v120, v120
	v_exp_f32_e32 v121, v121
	ds_read_b64_tr_b16 v[84:85], v207 offset:35840
	ds_read_b64_tr_b16 v[86:87], v207 offset:36352
	ds_read_b128 v[184:187], v4 offset:6144
	ds_read_b128 v[4:7], v4 offset:6656
	s_waitcnt lgkmcnt(14)
	v_mfma_f32_32x32x16_bf16 v[20:35], v[156:159], v[92:95], v[20:35]
	v_exp_f32_e32 v122, v122
	v_exp_f32_e32 v123, v123
	ds_read_b64_tr_b16 v[92:93], v207 offset:39936
	ds_read_b64_tr_b16 v[94:95], v207 offset:40448
	s_waitcnt lgkmcnt(12)
	v_mfma_f32_32x32x16_bf16 v[36:51], v[152:155], v[14:17], v[36:51]
	v_exp_f32_e32 v124, v124
	v_exp_f32_e32 v125, v125
	ds_read_b128 v[14:17], v219
	s_waitcnt lgkmcnt(9)
	v_mfma_f32_32x32x16_bf16 v[20:35], v[152:155], v[88:91], v[20:35]
	v_exp_f32_e32 v126, v126
	v_exp_f32_e32 v127, v127
	s_add_u32 s98, s100, s34
	s_addc_u32 s99, s101, s35
	s_lshl_b32 m0, s60, 14
	s_add_i32 m0, m0, s58
	s_addk_i32 m0, 0x2000
	s_nop 0
	global_load_lds_dwordx4 v255, s[98:99]
	s_waitcnt lgkmcnt(5)
	v_mfma_f32_32x32x16_bf16 v[36:51], v[148:151], v[84:87], v[36:51]
	v_exp_f32_e32 v128, v128
	v_exp_f32_e32 v129, v129
	s_waitcnt lgkmcnt(1)
	v_mfma_f32_32x32x16_bf16 v[20:35], v[148:151], v[92:95], v[20:35]
	v_exp_f32_e32 v130, v130
	v_exp_f32_e32 v131, v131
	s_waitcnt vmcnt(3) lgkmcnt(0)
	s_barrier
	s_add_i32 s16, s60, 1
	s_cmp_lg_u32 s60, 2
	s_cselect_b32 s59, s16, 0
	ds_read_b128 v[188:191], v219 offset:1024
	v_lshl_add_u32 v207, s10, 14, v214
	s_waitcnt lgkmcnt(1)
	v_mfma_f32_32x32x16_bf16 v[100:115], v[96:99], v[14:17], 0
	v_add_f32_e32 v84, v132, v133
	v_add_f32_e32 v84, v134, v84
	v_add_f32_e32 v84, v135, v84
	v_add_f32_e32 v84, v136, v84
	v_add_f32_e32 v84, v137, v84
	v_cvt_pk_bf16_f32 v160, v132, v133
	v_cvt_pk_bf16_f32 v161, v134, v135
	s_nop 0
	v_add_f32_e32 v84, v138, v84
	v_add_f32_e32 v84, v139, v84
	v_add_f32_e32 v84, v140, v84
	v_add_f32_e32 v148, v141, v84
	v_mfma_f32_32x32x16_bf16 v[84:99], v[164:167], v[14:17], 0
	v_cvt_pk_bf16_f32 v162, v136, v137
	v_cvt_pk_bf16_f32 v163, v138, v139
	ds_read_b128 v[14:17], v219 offset:2048
	ds_read_b64_tr_b16 v[132:133], v207 offset:24576
	ds_read_b64_tr_b16 v[134:135], v207 offset:25088
	s_waitcnt lgkmcnt(3)
	v_mfma_f32_32x32x16_bf16 v[100:115], v[168:171], v[188:191], v[100:115]
	v_add_f32_e32 v136, v142, v148
	v_add_f32_e32 v136, v143, v136
	v_add_f32_e32 v136, v144, v136
	v_add_f32_e32 v136, v145, v136
	v_cvt_pk_bf16_f32 v156, v140, v141
	v_cvt_pk_bf16_f32 v157, v142, v143
	v_mfma_f32_32x32x16_bf16 v[84:99], v[172:175], v[188:191], v[84:99]
	v_add_f32_e32 v136, v146, v136
	v_add_f32_e32 v136, v147, v136
	v_add_f32_e32 v136, v116, v136
	v_add_f32_e32 v148, v117, v136
	v_cvt_pk_bf16_f32 v158, v144, v145
	v_cvt_pk_bf16_f32 v159, v146, v147
	ds_read_b128 v[136:139], v219 offset:3072
	ds_read_b64_tr_b16 v[140:141], v207 offset:28672
	ds_read_b64_tr_b16 v[142:143], v207 offset:29184
	s_waitcnt lgkmcnt(5)
	v_mfma_f32_32x32x16_bf16 v[100:115], v[176:179], v[14:17], v[100:115]
	v_add_f32_e32 v144, v118, v148
	v_add_f32_e32 v144, v119, v144
	v_add_f32_e32 v144, v120, v144
	v_add_f32_e32 v144, v121, v144
	v_cvt_pk_bf16_f32 v152, v116, v117
	v_cvt_pk_bf16_f32 v153, v118, v119
	v_mfma_f32_32x32x16_bf16 v[84:99], v[180:183], v[14:17], v[84:99]
	v_add_f32_e32 v14, v122, v144
	v_add_f32_e32 v14, v123, v14
	v_add_f32_e32 v14, v124, v14
	v_add_f32_e32 v116, v125, v14
	v_cvt_pk_bf16_f32 v154, v120, v121
	v_cvt_pk_bf16_f32 v155, v122, v123
	ds_read_b64_tr_b16 v[14:15], v207 offset:25600
	ds_read_b64_tr_b16 v[16:17], v207 offset:26112
	s_waitcnt lgkmcnt(4)
	v_mfma_f32_32x32x16_bf16 v[100:115], v[184:187], v[136:139], v[100:115]
	v_add_f32_e32 v116, v126, v116
	v_add_f32_e32 v116, v127, v116
	v_add_f32_e32 v116, v128, v116
	v_add_f32_e32 v116, v129, v116
	v_cvt_pk_bf16_f32 v148, v124, v125
	v_cvt_pk_bf16_f32 v149, v126, v127
	v_mfma_f32_32x32x16_bf16 v[84:99], v[4:7], v[136:139], v[84:99]
	v_add_f32_e32 v4, v130, v116
	v_add_f32_e32 v4, v131, v4
	v_cvt_pk_bf16_f32 v150, v128, v129
	v_cvt_pk_bf16_f32 v151, v130, v131
	v_add_f32_e32 v225, v2, v4
	ds_read_b64_tr_b16 v[4:5], v207 offset:29696
	ds_read_b64_tr_b16 v[6:7], v207 offset:30208
	v_mfma_f32_32x32x16_bf16 v[68:83], v[160:163], v[132:135], v[68:83]
	v_exp_f32_e32 v100, v100
	v_exp_f32_e32 v101, v101
	ds_read_b64_tr_b16 v[10:11], v207 offset:26624
	ds_read_b64_tr_b16 v[12:13], v207 offset:27136
	s_waitcnt lgkmcnt(6)
	v_mfma_f32_32x32x16_bf16 v[52:67], v[160:163], v[140:143], v[52:67]
	v_exp_f32_e32 v102, v102
	v_exp_f32_e32 v103, v103
	s_add_u32 s98, s100, s36
	s_addc_u32 s99, s101, s37
	s_lshl_b32 m0, s60, 13
	s_add_i32 m0, m0, s49
	s_nop 0
	global_load_lds_dwordx4 v254, s[98:99]
	ds_read_b64_tr_b16 v[116:117], v207 offset:30720
	ds_read_b64_tr_b16 v[118:119], v207 offset:31232
	s_waitcnt lgkmcnt(6)
	v_mfma_f32_32x32x16_bf16 v[68:83], v[156:159], v[14:17], v[68:83]
	v_exp_f32_e32 v104, v104
	v_exp_f32_e32 v105, v105
	ds_read_b64_tr_b16 v[14:15], v207 offset:27648
	ds_read_b64_tr_b16 v[16:17], v207 offset:28160
	s_waitcnt lgkmcnt(6)
; #define TWAIT_BAR(N) asm volatile("s_waitcnt vmcnt(" #N ") lgkmcnt(0)\n\ts_barrier" ::: "memory")
; #define RESC() do { if constexpr (!NOMAX) if (resc) { asm volatile("s_waitcnt lgkmcnt(0)" ::: "memory"); \
;         _Pragma("unroll") for (int d_ = 0; d_ < 2; ++d_) _Pragma("unroll") for (int r = 0; r < 16; ++r) o[d_][r] *= wsf[crow(r, hi)]; } } while (0)
; #define ROT() do { sl_prev = sl_cur; sl_cur = sl_next; sl_next = (sl_next == 2 * SLOTB) ? 0 : sl_next + SLOTB; } while (0)
; #define RESC() do { if constexpr (!NOMAX) if (resc) { asm volatile("s_waitcnt lgkmcnt(0)" ::: "memory"); \
;         _Pragma("unroll") for (int d_ = 0; d_ < 4; ++d_) _Pragma("unroll") for (int r = 0; r < 16; ++r) o[d_][r] *= wsf[crow(r, hi)]; } } while (0)
; #define ROT() do { sl_prev = sl_cur; sl_cur = sl_next; sl_next = (sl_next == 2) ? 0 : sl_next + 1; } while (0)
; #define RESC() do { if (resc) { asm volatile("s_waitcnt lgkmcnt(0)" ::: "memory"); \
;         _Pragma("unroll") for (int d_ = 0; d_ < 4; ++d_) _Pragma("unroll") for (int r = 0; r < 16; ++r) o[d_][r] *= wsf[crow(r, hi)]; } } while (0)
; template <bool NOMAX>
; __device__ __forceinline__ void diff_unit(const AttnCtx& C, int u, LAS unsigned char* lds) {
;     ...
;     int kk = 1;
;     for (; kk + 7 < n; kk += 2) {
;         STEP(pB0, pB1, pA0, pA1, kk, true, true, true, false);     TWAIT_BAR(3); RESC(); ROT();
;         STEP(pA0, pA1, pB0, pB1, kk + 1, true, true, true, false); TWAIT_BAR(3); RESC(); ROT();
;     }
	v_mfma_f32_32x32x16_bf16 v[52:67], v[156:159], v[4:7], v[52:67]
	v_exp_f32_e32 v106, v106
	v_exp_f32_e32 v107, v107
	ds_read_b64_tr_b16 v[4:5], v207 offset:31744
	ds_read_b64_tr_b16 v[6:7], v207 offset:32256
	s_waitcnt lgkmcnt(6)
	v_mfma_f32_32x32x16_bf16 v[68:83], v[152:155], v[10:13], v[68:83]
	v_exp_f32_e32 v108, v108
	v_exp_f32_e32 v109, v109
	s_add_u32 s98, s100, s38
	s_addc_u32 s99, s101, s39
	s_lshl_b32 m0, s59, 14
	s_add_i32 m0, m0, s58
	s_nop 0
	global_load_lds_dwordx4 v255, s[98:99]
	ds_read_b64_tr_b16 v[10:11], v207 offset:32768
	ds_read_b64_tr_b16 v[12:13], v207 offset:33280
	s_waitcnt lgkmcnt(6)
	v_mfma_f32_32x32x16_bf16 v[52:67], v[152:155], v[116:119], v[52:67]
	v_exp_f32_e32 v110, v110
	v_exp_f32_e32 v111, v111
	ds_read_b64_tr_b16 v[116:117], v207 offset:36864
	ds_read_b64_tr_b16 v[118:119], v207 offset:37376
	s_waitcnt lgkmcnt(6)
	v_mfma_f32_32x32x16_bf16 v[68:83], v[148:151], v[14:17], v[68:83]
	v_exp_f32_e32 v112, v112
	v_exp_f32_e32 v113, v113
	ds_read_b64_tr_b16 v[14:15], v207 offset:33792
	ds_read_b64_tr_b16 v[16:17], v207 offset:34304
	s_waitcnt lgkmcnt(6)
	v_mfma_f32_32x32x16_bf16 v[52:67], v[148:151], v[4:7], v[52:67]
	v_exp_f32_e32 v114, v114
	v_exp_f32_e32 v115, v115
	ds_read_b64_tr_b16 v[4:5], v207 offset:37888
	ds_read_b64_tr_b16 v[6:7], v207 offset:38400
	v_lshl_add_u32 v2, s59, 13, v222
	ds_read_b128 v[192:195], v2
	ds_read_b128 v[184:187], v2 offset:512
	s_waitcnt lgkmcnt(8)
	v_mfma_f32_32x32x16_bf16 v[36:51], v[160:163], v[10:13], v[36:51]
	v_exp_f32_e32 v84, v84
	v_exp_f32_e32 v85, v85
	ds_read_b64_tr_b16 v[10:11], v207 offset:34816
	ds_read_b64_tr_b16 v[12:13], v207 offset:35328
	ds_read_b128 v[188:191], v2 offset:2048
	ds_read_b128 v[180:183], v2 offset:2560
	s_waitcnt lgkmcnt(10)
	v_mfma_f32_32x32x16_bf16 v[20:35], v[160:163], v[116:119], v[20:35]
	v_exp_f32_e32 v86, v86
	v_exp_f32_e32 v87, v87
	ds_read_b64_tr_b16 v[120:121], v207 offset:38912
	ds_read_b64_tr_b16 v[122:123], v207 offset:39424
	ds_read_b128 v[176:179], v2 offset:4096
	ds_read_b128 v[172:175], v2 offset:4608
	s_waitcnt lgkmcnt(12)
	v_mfma_f32_32x32x16_bf16 v[36:51], v[156:159], v[14:17], v[36:51]
	v_exp_f32_e32 v88, v88
	v_exp_f32_e32 v89, v89
	ds_read_b64_tr_b16 v[14:15], v207 offset:35840
	ds_read_b64_tr_b16 v[16:17], v207 offset:36352
	ds_read_b128 v[168:171], v2 offset:6144
	ds_read_b128 v[164:167], v2 offset:6656
	s_waitcnt lgkmcnt(14)
	v_mfma_f32_32x32x16_bf16 v[20:35], v[156:159], v[4:7], v[20:35]
	v_exp_f32_e32 v90, v90
	v_exp_f32_e32 v91, v91
	ds_read_b64_tr_b16 v[4:5], v207 offset:39936
	ds_read_b64_tr_b16 v[6:7], v207 offset:40448
	s_waitcnt lgkmcnt(12)
	v_mfma_f32_32x32x16_bf16 v[36:51], v[152:155], v[10:13], v[36:51]
	v_exp_f32_e32 v92, v92
	v_exp_f32_e32 v93, v93
	ds_read_b128 v[116:119], v219
	s_waitcnt lgkmcnt(9)
	v_mfma_f32_32x32x16_bf16 v[20:35], v[152:155], v[120:123], v[20:35]
	v_exp_f32_e32 v94, v94
	v_exp_f32_e32 v95, v95
	s_add_u32 s98, s100, s40
	s_addc_u32 s99, s101, s41
	s_lshl_b32 m0, s59, 14
	s_add_i32 m0, m0, s58
	s_addk_i32 m0, 0x2000
	s_nop 0
	global_load_lds_dwordx4 v255, s[98:99]
	s_waitcnt lgkmcnt(5)
	v_mfma_f32_32x32x16_bf16 v[36:51], v[148:151], v[14:17], v[36:51]
	v_exp_f32_e32 v96, v96
	v_exp_f32_e32 v97, v97
	s_waitcnt lgkmcnt(1)
	v_mfma_f32_32x32x16_bf16 v[20:35], v[148:151], v[4:7], v[20:35]
	v_exp_f32_e32 v98, v98
	v_exp_f32_e32 v99, v99
	s_add_i32 s10, s59, 1
	s_cmp_lg_u32 s59, 2
	s_waitcnt vmcnt(3) lgkmcnt(0)
	s_barrier
	s_cselect_b32 s60, s10, 0
	s_add_i32 s16, s9, 2
	s_add_u32 s6, s6, 0x20000
	v_cmp_ge_u32_e32 vcc, s16, v226
	s_addc_u32 s7, s7, 0
	s_add_u32 s100, s100, 0x20000
	s_addc_u32 s101, s101, 0
	s_mov_b32 s11, s8
	s_cbranch_vccz .LBB0_463
	s_add_i32 s16, s9, -5
	s_branch .LBB0_467
